# v79 + O3 kv-up k_nope rows staged through LDS and stored as 16-byte row chunks
# speedup vs baseline: 1.0037x; 1.0037x over previous
.LBB0_505:
	v_lshlrev_b32_e32 v88, 5, v87
	v_mov_b32_e32 v89, v129
	v_lshl_add_u64 v[68:69], v[66:67], 0, v[88:89]
	global_load_dwordx4 v[72:75], v[68:69], off offset:64
	global_load_dwordx4 v[64:67], v[68:69], off offset:80
	global_load_dwordx4 v[76:79], v[68:69], off
	s_nop 0
	global_load_dwordx4 v[68:71], v[68:69], off offset:16
	v_lshlrev_b32_e32 v83, 4, v87
	v_pk_mul_f32 v[92:93], v[40:41], v[86:87] op_sel_hi:[1,0]
	v_pk_mul_f32 v[90:91], v[42:43], v[86:87] op_sel_hi:[1,0]
	v_pk_mul_f32 v[42:43], v[44:45], v[86:87] op_sel_hi:[1,0]
	v_pk_mul_f32 v[40:41], v[46:47], v[86:87] op_sel_hi:[1,0]
	v_pk_mul_f32 v[44:45], v[50:51], v[86:87] op_sel_hi:[1,0]
	v_pk_mul_f32 v[46:47], v[48:49], v[86:87] op_sel_hi:[1,0]
	v_pk_mul_f32 v[48:49], v[54:55], v[86:87] op_sel_hi:[1,0]
	v_pk_mul_f32 v[50:51], v[52:53], v[86:87] op_sel_hi:[1,0]
	v_pk_mul_f32 v[52:53], v[58:59], v[86:87] op_sel_hi:[1,0]
	v_pk_mul_f32 v[54:55], v[56:57], v[86:87] op_sel_hi:[1,0]
	v_pk_mul_f32 v[56:57], v[62:63], v[86:87] op_sel_hi:[1,0]
	v_pk_mul_f32 v[58:59], v[60:61], v[86:87] op_sel_hi:[1,0]
	v_pk_mul_f32 v[60:61], v[34:35], v[86:87] op_sel_hi:[1,0]
	v_pk_mul_f32 v[62:63], v[32:33], v[86:87] op_sel_hi:[1,0]
	global_load_dwordx4 v[198:201], v83, s[40:41]
	global_load_dwordx4 v[202:205], v83, s[40:41] offset:32
	global_load_dwordx4 v[206:209], v83, s[40:41] offset:64
	global_load_dwordx4 v[210:213], v83, s[40:41] offset:96
	global_load_dwordx4 v[214:217], v83, s[40:41] offset:128
	global_load_dwordx4 v[218:221], v83, s[40:41] offset:160
	global_load_dwordx4 v[222:225], v83, s[40:41] offset:192
	global_load_dwordx4 v[226:229], v83, s[40:41] offset:224
	global_load_dwordx2 v[230:231], v88, s[40:41] offset:320
	global_load_dwordx2 v[232:233], v88, s[40:41] offset:256
	global_load_dword v185, v88, s[40:41] offset:264
	global_load_dword v184, v88, s[40:41] offset:328
	global_load_dword v187, v88, s[40:41] offset:268
	global_load_dword v186, v88, s[40:41] offset:332
	global_load_dword v189, v88, s[40:41] offset:272
	global_load_dword v188, v88, s[40:41] offset:336
	global_load_dword v191, v88, s[40:41] offset:276
	global_load_dword v190, v88, s[40:41] offset:340
	global_load_dword v193, v88, s[40:41] offset:280
	global_load_dword v192, v88, s[40:41] offset:344
	global_load_dword v235, v88, s[40:41] offset:284
	global_load_dword v234, v88, s[40:41] offset:348
	v_pk_mul_f32 v[96:97], v[36:37], v[86:87] op_sel_hi:[1,0]
	v_mul_f32_e32 v36, v47, v47
	v_pk_fma_f32 v[36:37], v[46:47], v[46:47], v[36:37] op_sel_hi:[1,1,0]
	v_mul_f32_e32 v98, v45, v45
	v_pk_fma_f32 v[36:37], v[44:45], v[44:45], v[36:37]
	v_mul_f32_e32 v100, v51, v51
	v_pk_add_f32 v[36:37], v[98:99], v[36:37] op_sel_hi:[0,1]
	v_pk_fma_f32 v[36:37], v[50:51], v[50:51], v[36:37]
	v_mul_f32_e32 v102, v49, v49
	v_pk_add_f32 v[36:37], v[100:101], v[36:37] op_sel_hi:[0,1]
	v_pk_fma_f32 v[36:37], v[48:49], v[48:49], v[36:37]
	v_mul_f32_e32 v104, v55, v55
	v_pk_add_f32 v[36:37], v[102:103], v[36:37] op_sel_hi:[0,1]
	v_pk_fma_f32 v[36:37], v[54:55], v[54:55], v[36:37]
	v_mul_f32_e32 v106, v53, v53
	v_pk_add_f32 v[36:37], v[104:105], v[36:37] op_sel_hi:[0,1]
	v_pk_fma_f32 v[36:37], v[52:53], v[52:53], v[36:37]
	v_mul_f32_e32 v108, v59, v59
	v_pk_add_f32 v[36:37], v[106:107], v[36:37] op_sel_hi:[0,1]
	v_pk_fma_f32 v[36:37], v[58:59], v[58:59], v[36:37]
	v_mul_f32_e32 v110, v57, v57
	v_pk_add_f32 v[36:37], v[108:109], v[36:37] op_sel_hi:[0,1]
	v_pk_fma_f32 v[36:37], v[56:57], v[56:57], v[36:37]
	v_mul_f32_e32 v112, v63, v63
	v_pk_add_f32 v[36:37], v[110:111], v[36:37] op_sel_hi:[0,1]
	v_pk_fma_f32 v[36:37], v[62:63], v[62:63], v[36:37]
	v_mul_f32_e32 v114, v61, v61
	v_pk_add_f32 v[36:37], v[112:113], v[36:37] op_sel_hi:[0,1]
	v_pk_fma_f32 v[36:37], v[60:61], v[60:61], v[36:37]
	v_mul_f32_e32 v116, v97, v97
	v_pk_add_f32 v[36:37], v[114:115], v[36:37] op_sel_hi:[0,1]
	v_pk_fma_f32 v[36:37], v[96:97], v[96:97], v[36:37]
	v_pk_mul_f32 v[38:39], v[38:39], v[86:87] op_sel_hi:[1,0]
	v_pk_add_f32 v[36:37], v[116:117], v[36:37] op_sel_hi:[0,1]
	v_mul_f32_e32 v118, v39, v39
	v_pk_fma_f32 v[36:37], v[38:39], v[38:39], v[36:37]
	v_mul_f32_e32 v120, v93, v93
	v_pk_add_f32 v[36:37], v[118:119], v[36:37] op_sel_hi:[0,1]
	v_pk_fma_f32 v[36:37], v[92:93], v[92:93], v[36:37]
	v_mul_f32_e32 v122, v91, v91
	v_pk_add_f32 v[36:37], v[120:121], v[36:37] op_sel_hi:[0,1]
	v_pk_fma_f32 v[36:37], v[90:91], v[90:91], v[36:37]
	v_mul_f32_e32 v124, v43, v43
	v_pk_add_f32 v[36:37], v[122:123], v[36:37] op_sel_hi:[0,1]
	v_pk_fma_f32 v[36:37], v[42:43], v[42:43], v[36:37]
	v_mul_f32_e32 v126, v41, v41
	v_pk_add_f32 v[36:37], v[124:125], v[36:37] op_sel_hi:[0,1]
	v_pk_fma_f32 v[36:37], v[40:41], v[40:41], v[36:37]
	s_mov_b32 s2, 0x800000
	v_pk_add_f32 v[36:37], v[126:127], v[36:37] op_sel_hi:[0,1]
	v_mov_b32_e32 v98, v36
	s_nop 1
	v_permlane32_swap_b32_e32 v36, v98
	v_lshlrev_b32_e32 v128, 3, v87
	s_waitcnt vmcnt(25)
	v_pk_mul_f32 v[102:103], v[72:73], v[72:73]
	v_pk_mul_f32 v[100:101], v[74:75], v[74:75]
	s_waitcnt vmcnt(23)
	v_pk_fma_f32 v[102:103], v[76:77], v[76:77], v[102:103]
	v_pk_fma_f32 v[100:101], v[78:79], v[78:79], v[100:101]
	v_pk_add_f32 v[102:103], v[102:103], v[102:103] op_sel:[0,1] op_sel_hi:[1,0]
	v_pk_mul_f32 v[106:107], v[64:65], v[64:65]
	v_pk_add_f32 v[102:103], v[100:101], v[102:103]
	s_waitcnt vmcnt(22)
	v_pk_fma_f32 v[106:107], v[68:69], v[68:69], v[106:107]
	v_pk_add_f32 v[100:101], v[100:101], v[102:103] op_sel:[1,0] op_sel_hi:[0,1]
	v_pk_mul_f32 v[104:105], v[66:67], v[66:67]
	v_pk_add_f32 v[100:101], v[106:107], v[100:101]
	v_pk_fma_f32 v[104:105], v[70:71], v[70:71], v[104:105]
	v_pk_add_f32 v[100:101], v[106:107], v[100:101] op_sel:[1,0] op_sel_hi:[0,1]
	v_pk_add_f32 v[100:101], v[104:105], v[100:101]
	s_nop 0
	v_pk_add_f32 v[100:101], v[104:105], v[100:101] op_sel:[1,0] op_sel_hi:[0,1]
	v_mov_b32_e32 v99, v100
	s_nop 1
	v_permlane32_swap_b32_e32 v100, v99
	v_mov_b32_e32 v37, v100
	v_pk_add_f32 v[36:37], v[36:37], v[98:99]
	v_lshl_add_u64 v[98:99], v[84:85], 0, v[128:129]
	v_add_f32_e32 v36, v36, v37
	v_fmamk_f32 v36, v36, 0x3c2aaaab, v163
	v_mul_f32_e32 v37, 0x4b800000, v36
	v_cmp_gt_f32_e32 vcc, s2, v36
	s_nop 1
	v_cndmask_b32_e32 v36, v36, v37, vcc
	v_rsq_f32_e32 v36, v36
	s_nop 0
	v_mul_f32_e32 v37, 0x45800000, v36
	v_cndmask_b32_e32 v36, v36, v37, vcc
	v_pk_mul_f32 v[46:47], v[46:47], v[36:37] op_sel_hi:[1,0]
	v_pk_mul_f32 v[44:45], v[44:45], v[36:37] op_sel_hi:[1,0]
	s_waitcnt vmcnt(21)
	v_pk_mul_f32 v[32:33], v[198:199], v[46:47]
	v_pk_mul_f32 v[34:35], v[200:201], v[44:45]
	v_cvt_pk_bf16_f32 v32, v32, v33
	v_cvt_pk_bf16_f32 v33, v34, v35
	v_and_b32_e32 v240, 31, v155
	v_bfe_u32 v243, v155, 3, 3
	v_lshrrev_b32_e32 v239, 6, v155
	v_mul_u32_u24_e32 v239, 0x1400, v239
	v_add_u32_e32 v239, 0xc000, v239
	v_mul_u32_u24_e32 v238, 0x90, v240
	v_mul_u32_u24_e32 v244, 0x90, v243
	v_add_u32_e32 v238, v238, v239
	v_add_u32_e32 v239, v244, v239
	v_sub_u32_e32 v244, v243, v240
	v_mul_i32_i24_e32 v244, 0xc0, v244
	v_and_b32_e32 v243, 7, v155
	v_lshl_add_u32 v239, v243, 4, v239
	v_lshl_add_u32 v244, v243, 4, v244
	v_bfe_u32 v243, v155, 5, 1
	v_lshl_add_u32 v238, v243, 3, v238
	v_lshlrev_b32_e32 v243, 3, v243
	v_sub_u32_e32 v244, v244, v243
	v_ashrrev_i32_e32 v245, 31, v244
	v_lshl_add_u64 v[236:237], v[98:99], 0, v[244:245]
	ds_write_b64 v238, v[32:33]
	v_pk_mul_f32 v[44:45], v[50:51], v[36:37] op_sel_hi:[1,0]
	v_pk_mul_f32 v[46:47], v[48:49], v[36:37] op_sel_hi:[1,0]
	v_pk_mul_f32 v[38:39], v[38:39], v[36:37] op_sel_hi:[1,0]
	v_pk_mul_f32 v[40:41], v[40:41], v[36:37] op_sel_hi:[1,0]
	v_cmp_gt_u32_e32 vcc, 32, v94
	s_waitcnt vmcnt(20)
	v_pk_mul_f32 v[32:33], v[202:203], v[44:45]
	v_pk_mul_f32 v[34:35], v[204:205], v[46:47]
	v_cvt_pk_bf16_f32 v32, v32, v33
	v_cvt_pk_bf16_f32 v33, v34, v35
	ds_write_b64 v238, v[32:33] offset:16
	v_pk_mul_f32 v[44:45], v[54:55], v[36:37] op_sel_hi:[1,0]
	v_pk_mul_f32 v[46:47], v[52:53], v[36:37] op_sel_hi:[1,0]
	s_waitcnt vmcnt(19)
	v_pk_mul_f32 v[32:33], v[206:207], v[44:45]
	v_pk_mul_f32 v[34:35], v[208:209], v[46:47]
	v_cvt_pk_bf16_f32 v32, v32, v33
	v_cvt_pk_bf16_f32 v33, v34, v35
	ds_write_b64 v238, v[32:33] offset:32
	v_pk_mul_f32 v[44:45], v[58:59], v[36:37] op_sel_hi:[1,0]
	v_pk_mul_f32 v[46:47], v[56:57], v[36:37] op_sel_hi:[1,0]
	s_waitcnt vmcnt(18)
	v_pk_mul_f32 v[32:33], v[210:211], v[44:45]
	v_pk_mul_f32 v[34:35], v[212:213], v[46:47]
	v_cvt_pk_bf16_f32 v32, v32, v33
	v_cvt_pk_bf16_f32 v33, v34, v35
	ds_write_b64 v238, v[32:33] offset:48
	v_pk_mul_f32 v[44:45], v[62:63], v[36:37] op_sel_hi:[1,0]
	v_pk_mul_f32 v[46:47], v[60:61], v[36:37] op_sel_hi:[1,0]
	s_waitcnt vmcnt(17)
	v_pk_mul_f32 v[32:33], v[214:215], v[44:45]
	v_pk_mul_f32 v[34:35], v[216:217], v[46:47]
	v_cvt_pk_bf16_f32 v32, v32, v33
	v_cvt_pk_bf16_f32 v33, v34, v35
	ds_write_b64 v238, v[32:33] offset:64
	v_pk_mul_f32 v[44:45], v[96:97], v[36:37] op_sel_hi:[1,0]
	s_waitcnt vmcnt(16)
	v_pk_mul_f32 v[34:35], v[38:39], v[220:221]
	v_pk_mul_f32 v[32:33], v[44:45], v[218:219]
	v_pk_mul_f32 v[38:39], v[92:93], v[36:37] op_sel_hi:[1,0]
	v_cvt_pk_bf16_f32 v32, v32, v33
	v_cvt_pk_bf16_f32 v33, v34, v35
	ds_write_b64 v238, v[32:33] offset:80
	v_pk_mul_f32 v[44:45], v[90:91], v[36:37] op_sel_hi:[1,0]
	s_waitcnt vmcnt(15)
	v_pk_mul_f32 v[32:33], v[38:39], v[222:223]
	v_pk_mul_f32 v[34:35], v[44:45], v[224:225]
	v_cvt_pk_bf16_f32 v32, v32, v33
	v_cvt_pk_bf16_f32 v33, v34, v35
	ds_write_b64 v238, v[32:33] offset:96
	v_pk_mul_f32 v[38:39], v[42:43], v[36:37] op_sel_hi:[1,0]
	s_waitcnt vmcnt(14)
	v_pk_mul_f32 v[34:35], v[40:41], v[228:229]
	v_pk_mul_f32 v[32:33], v[38:39], v[226:227]
	s_nop 0
	v_cvt_pk_bf16_f32 v32, v32, v33
	v_cvt_pk_bf16_f32 v33, v34, v35
	ds_write_b64 v238, v[32:33] offset:112
	s_waitcnt lgkmcnt(0)
	s_mov_b64 s[2:3], 0x600
	ds_read_b128 v[194:197], v239
	ds_read_b128 v[244:247], v239 offset:1152
	s_waitcnt lgkmcnt(1)
	global_store_dwordx4 v[236:237], v[194:197], off
	v_lshl_add_u64 v[236:237], v[236:237], 0, s[2:3]
	s_nop 4
	ds_read_b128 v[194:197], v239 offset:2304
	s_waitcnt lgkmcnt(1)
	global_store_dwordx4 v[236:237], v[244:247], off
	v_lshl_add_u64 v[236:237], v[236:237], 0, s[2:3]
	s_nop 4
	ds_read_b128 v[244:247], v239 offset:3456
	s_waitcnt lgkmcnt(1)
	global_store_dwordx4 v[236:237], v[194:197], off
	v_lshl_add_u64 v[236:237], v[236:237], 0, s[2:3]
	s_waitcnt lgkmcnt(0)
	global_store_dwordx4 v[236:237], v[244:247], off
	v_lshrrev_b32_e32 v32, 6, v95
	v_and_b32_e32 v33, 63, v95
	v_cndmask_b32_e32 v32, v33, v32, vcc
	v_cvt_f32_u32_e32 v52, v32
	v_mov_b32_e32 v32, v73
	v_mov_b32_e32 v33, v77
	v_pk_mul_f32 v[32:33], v[32:33], v[36:37] op_sel_hi:[1,0]
	s_waitcnt vmcnt(17)
	v_mov_b32_e32 v34, v231
	s_waitcnt vmcnt(16)
	v_mov_b32_e32 v35, v233
	v_pk_mul_f32 v[32:33], v[32:33], v[34:35]
	s_and_saveexec_b64 s[2:3], s[0:1]
	s_cbranch_execz .LBB0_507
	v_mul_f32_e32 v34, v156, v52
	v_mul_f32_e32 v35, 0.15915494, v34
	v_sin_f32_e32 v38, v35
	v_cos_f32_e32 v34, v35
	v_pk_mul_f32 v[38:39], v[38:39], v[32:33] op_sel:[0,1] op_sel_hi:[0,0]
	v_pk_mul_f32 v[40:41], v[34:35], v[32:33] op_sel_hi:[0,1]
	v_pk_fma_f32 v[32:33], v[34:35], v[32:33], v[38:39] op_sel_hi:[0,1,1] neg_lo:[0,0,1] neg_hi:[0,0,1]
	v_add_f32_e32 v32, v40, v38
.LBB0_507:
	s_or_b64 exec, exec, s[2:3]
	v_mov_b32_e32 v37, v36
	v_mov_b32_e32 v38, v74
	v_mov_b32_e32 v39, v78
	v_pk_mul_f32 v[38:39], v[38:39], v[36:37]
	s_waitcnt vmcnt(14)
	v_pk_mul_f32 v[34:35], v[38:39], v[184:185]
	s_and_saveexec_b64 s[2:3], s[0:1]
	s_cbranch_execz .LBB0_509
	v_mul_f32_e32 v38, v157, v52
	v_mul_f32_e32 v39, 0.15915494, v38
	v_sin_f32_e32 v40, v39
	v_cos_f32_e32 v38, v39
	v_pk_mul_f32 v[40:41], v[40:41], v[34:35] op_sel:[0,1] op_sel_hi:[0,0]
	v_pk_mul_f32 v[42:43], v[38:39], v[34:35] op_sel_hi:[0,1]
	v_pk_fma_f32 v[34:35], v[38:39], v[34:35], v[40:41] op_sel_hi:[0,1,1] neg_lo:[0,0,1] neg_hi:[0,0,1]
	v_add_f32_e32 v34, v42, v40
.LBB0_509:
	s_or_b64 exec, exec, s[2:3]
	v_mov_b32_e32 v78, v75
	v_pk_mul_f32 v[40:41], v[78:79], v[36:37]
	s_waitcnt vmcnt(12)
	v_pk_mul_f32 v[38:39], v[40:41], v[186:187]
	s_and_saveexec_b64 s[2:3], s[0:1]
	s_cbranch_execz .LBB0_511
	v_mul_f32_e32 v40, v158, v52
	v_mul_f32_e32 v41, 0.15915494, v40
	v_sin_f32_e32 v42, v41
	v_cos_f32_e32 v40, v41
	v_pk_mul_f32 v[42:43], v[42:43], v[38:39] op_sel:[0,1] op_sel_hi:[0,0]
	v_pk_mul_f32 v[50:51], v[40:41], v[38:39] op_sel_hi:[0,1]
	v_pk_fma_f32 v[38:39], v[40:41], v[38:39], v[42:43] op_sel_hi:[0,1,1] neg_lo:[0,0,1] neg_hi:[0,0,1]
	v_add_f32_e32 v38, v50, v42
.LBB0_511:
	s_or_b64 exec, exec, s[2:3]
	v_mov_b32_e32 v42, v64
	v_mov_b32_e32 v43, v68
	v_pk_mul_f32 v[42:43], v[42:43], v[36:37]
	s_waitcnt vmcnt(10)
	v_pk_mul_f32 v[40:41], v[42:43], v[188:189]
	s_and_saveexec_b64 s[2:3], s[0:1]
	s_cbranch_execz .LBB0_513
	v_mul_f32_e32 v42, v159, v52
	v_mul_f32_e32 v43, 0.15915494, v42
	v_sin_f32_e32 v50, v43
	v_cos_f32_e32 v42, v43
	v_pk_mul_f32 v[50:51], v[50:51], v[40:41] op_sel:[0,1] op_sel_hi:[0,0]
	v_pk_mul_f32 v[54:55], v[42:43], v[40:41] op_sel_hi:[0,1]
	v_pk_fma_f32 v[40:41], v[42:43], v[40:41], v[50:51] op_sel_hi:[0,1,1] neg_lo:[0,0,1] neg_hi:[0,0,1]
	v_add_f32_e32 v40, v54, v50
.LBB0_513:
	s_or_b64 exec, exec, s[2:3]
	v_mov_b32_e32 v68, v65
	v_pk_mul_f32 v[50:51], v[68:69], v[36:37]
	s_waitcnt vmcnt(8)
	v_pk_mul_f32 v[42:43], v[50:51], v[190:191]
	s_and_saveexec_b64 s[2:3], s[0:1]
	s_cbranch_execz .LBB0_515
	v_mul_f32_e32 v45, v160, v52
	v_mul_f32_e32 v45, 0.15915494, v45
	v_sin_f32_e32 v54, v45
	v_cos_f32_e32 v50, v45
	v_pk_mul_f32 v[54:55], v[54:55], v[42:43] op_sel:[0,1] op_sel_hi:[0,0]
	v_pk_mul_f32 v[56:57], v[50:51], v[42:43] op_sel_hi:[0,1]
	v_pk_fma_f32 v[42:43], v[50:51], v[42:43], v[54:55] op_sel_hi:[0,1,1] neg_lo:[0,0,1] neg_hi:[0,0,1]
	v_add_f32_e32 v42, v56, v54
.LBB0_515:
	s_or_b64 exec, exec, s[2:3]
	v_mov_b32_e32 v54, v66
	v_mov_b32_e32 v55, v70
	v_pk_mul_f32 v[54:55], v[54:55], v[36:37]
	s_waitcnt vmcnt(6)
	v_pk_mul_f32 v[50:51], v[54:55], v[192:193]
	s_and_saveexec_b64 s[2:3], s[0:1]
	s_cbranch_execz .LBB0_517
	v_mul_f32_e32 v45, v161, v52
	v_mul_f32_e32 v45, 0.15915494, v45
	v_sin_f32_e32 v56, v45
	v_cos_f32_e32 v54, v45
	v_pk_mul_f32 v[56:57], v[56:57], v[50:51] op_sel:[0,1] op_sel_hi:[0,0]
	v_pk_mul_f32 v[58:59], v[54:55], v[50:51] op_sel_hi:[0,1]
	v_pk_fma_f32 v[50:51], v[54:55], v[50:51], v[56:57] op_sel_hi:[0,1,1] neg_lo:[0,0,1] neg_hi:[0,0,1]
	v_add_f32_e32 v50, v58, v56
.LBB0_517:
	s_or_b64 exec, exec, s[2:3]
	v_mov_b32_e32 v44, v230
	v_mov_b32_e32 v45, v232
	v_mov_b32_e32 v73, v76
	v_mov_b32_e32 v70, v67
	v_pk_mul_f32 v[54:55], v[72:73], v[36:37]
	v_pk_mul_f32 v[36:37], v[70:71], v[36:37]
	v_pk_mul_f32 v[44:45], v[54:55], v[44:45]
	s_waitcnt vmcnt(4)
	v_pk_mul_f32 v[36:37], v[36:37], v[234:235]
	s_and_saveexec_b64 s[2:3], s[0:1]
	s_cbranch_execz .LBB0_445
	v_mul_f32_e32 v47, 0.15915494, v52
	v_sin_f32_e32 v48, v47
	v_cos_f32_e32 v46, v47
	v_pk_mul_f32 v[48:49], v[48:49], v[44:45] op_sel:[0,1] op_sel_hi:[0,0]
	v_pk_mul_f32 v[54:55], v[46:47], v[44:45] op_sel_hi:[0,1]
	v_pk_fma_f32 v[44:45], v[46:47], v[44:45], v[48:49] op_sel_hi:[0,1,1] neg_lo:[0,0,1] neg_hi:[0,0,1]
	v_mul_f32_e32 v44, v162, v52
	v_mul_f32_e32 v46, 0.15915494, v44
	v_cos_f32_e32 v44, v46
	v_sin_f32_e32 v46, v46
	v_pk_mul_f32 v[52:53], v[44:45], v[36:37] op_sel_hi:[0,1]
	v_pk_mul_f32 v[46:47], v[46:47], v[36:37] op_sel:[0,1] op_sel_hi:[0,0]
	v_pk_fma_f32 v[36:37], v[44:45], v[36:37], v[46:47] op_sel_hi:[0,1,1] neg_lo:[0,0,1] neg_hi:[0,0,1]
	v_add_f32_e32 v44, v54, v48
	v_add_f32_e32 v36, v52, v46
	s_branch .LBB0_445
